# phase 6 dual mainloops now double-buffer the shared weight tile in LDS (64 KiB: W x2, A0, A1), one barrier pair per K-step
# speedup vs baseline: 1.1136x; 1.0042x over previous
.Lp6_dec:
	s_load_dwordx2 s[22:23], s[0:1], 0x60
	s_load_dwordx2 s[24:25], s[0:1], 0xe0
	s_load_dwordx2 s[26:27], s[0:1], 0xd8
	s_mov_b32 s3, 0x7fff
	v_mov_b32_e32 v242, 1
	v_lshlrev_b32_e32 v243, 4, v168
	v_bfe_u32 v249, v168, 6, 1
	v_bfe_u32 v250, v168, 4, 2
	v_lshlrev_b32_e32 v250, 4, v250
	v_lshl_or_b32 v244, v249, 8, v250
	s_lshl_b32 s71, s74, 9
	s_lshl_b32 s72, s2, 16
	s_waitcnt lgkmcnt(0)
	s_add_u32 s22, s22, s71
	s_addc_u32 s23, s23, 0
	s_add_u32 s24, s24, s72
	s_addc_u32 s25, s25, 0
	v_and_b32_e32 v236, 15, v168
	v_lshrrev_b32_e32 v237, 1, v236
	v_bfe_u32 v238, v168, 4, 2
	v_xor_b32_e32 v237, v237, v238
	v_lshlrev_b32_e32 v237, 4, v237
	v_lshl_or_b32 v236, v236, 7, v237
	v_xor_b32_e32 v237, 64, v236
	v_add_u32_e32 v236, 16, v236
	v_add_u32_e32 v237, 16, v237
	v_bfe_u32 v238, v168, 7, 1
	v_lshl_add_u32 v240, v238, 13, v237
	v_lshl_add_u32 v238, v238, 13, v236
	v_bfe_u32 v239, v168, 6, 1
	v_lshl_add_u32 v241, v239, 13, v237
	v_lshl_add_u32 v239, v239, 13, v236
	v_lshrrev_b32_e32 v236, 3, v168
	v_lshrrev_b32_e32 v237, 4, v168
	v_xor_b32_e32 v237, v237, v168
	v_and_b32_e32 v237, 7, v237
	v_lshlrev_b32_e32 v237, 4, v237
	v_lshl_or_b32 v232, v236, 11, v237
	v_add_u32_e32 v233, 0x10000, v232
	v_add_u32_e32 v234, 0x20000, v232
	v_add_u32_e32 v235, 0x30000, v232
	s_load_dwordx2 s[90:91], s[0:1], 0xa0
	s_load_dwordx2 s[92:93], s[0:1], 0xa8
	v_lshrrev_b32_e32 v237, 6, v168
	s_nop 1
	v_readfirstlane_b32 s97, v237
	s_nop 3
	s_lshl_b32 s96, s97, 10
	s_add_u32 s96, s96, 16
	s_add_u32 s94, s81, s80
	s_cmp_lt_i32 s94, s82
	s_cselect_b32 s95, 1, 0
	s_cmp_lg_u64 s[20:21], 0
	s_cselect_b32 s95, 0, s95
	s_cmp_ge_u32 s94, 0x40
	s_cselect_b32 s97, 1, 0
	s_mul_i32 s100, s97, 0x40
	s_sub_u32 s100, s94, s100
	s_lshr_b32 s101, s100, 3
	s_and_b32 s100, s100, 7
	s_lshl_b32 s97, s97, 3
	s_add_u32 s100, s100, s97
	s_add_u32 s100, s100, s79
	s_cmp_lg_u32 s101, s74
	s_cselect_b32 s95, 0, s95
	s_cmp_eq_u32 s95, 1
	s_cselect_b32 s101, s100, s70
	s_mov_b32 s97, s101
	s_waitcnt lgkmcnt(0)
	s_lshl_b32 s94, s74, 18
	s_add_u32 s94, s94, 0xc40000
	s_add_u32 s98, s92, s94
	s_addc_u32 s99, s93, 0
	s_lshl_b32 s101, s101, 18
	s_add_u32 s92, s90, s101
	s_addc_u32 s93, s91, 0
	s_lshl_b32 s94, s70, 18
	s_add_u32 s90, s90, s94
	s_addc_u32 s91, s91, 0
	s_mov_b64 s[100:101], s[90:91]
	s_mov_b64 s[90:91], s[98:99]
	s_mov_b64 s[98:99], s[92:93]
	s_mov_b64 s[92:93], s[100:101]
	s_waitcnt vmcnt(0)
	s_barrier
	s_add_u32 m0, s96, 0x0
	s_nop 0
	global_load_lds_dwordx4 v232, s[90:91]
	s_add_u32 m0, s96, 0x1000
	s_nop 0
	global_load_lds_dwordx4 v233, s[90:91]
	s_add_u32 m0, s96, 0x2000
	s_nop 0
	global_load_lds_dwordx4 v234, s[90:91]
	s_add_u32 m0, s96, 0x3000
	s_nop 0
	global_load_lds_dwordx4 v235, s[90:91]
	s_add_u32 m0, s96, 0x8000
	s_nop 0
	global_load_lds_dwordx4 v232, s[92:93]
	s_add_u32 m0, s96, 0x9000
	s_nop 0
	global_load_lds_dwordx4 v233, s[92:93]
	s_add_u32 m0, s96, 0xa000
	s_nop 0
	global_load_lds_dwordx4 v234, s[92:93]
	s_add_u32 m0, s96, 0xb000
	s_nop 0
	global_load_lds_dwordx4 v235, s[92:93]
	s_add_u32 m0, s96, 0xc000
	s_nop 0
	global_load_lds_dwordx4 v232, s[98:99]
	s_add_u32 m0, s96, 0xd000
	s_nop 0
	global_load_lds_dwordx4 v233, s[98:99]
	s_add_u32 m0, s96, 0xe000
	s_nop 0
	global_load_lds_dwordx4 v234, s[98:99]
	s_add_u32 m0, s96, 0xf000
	s_nop 0
	global_load_lds_dwordx4 v235, s[98:99]
	s_add_u32 s90, s90, 0x80
	s_addc_u32 s91, s91, 0
	s_add_u32 s92, s92, 0x80
	s_addc_u32 s93, s93, 0
	s_add_u32 s98, s98, 0x80
	s_addc_u32 s99, s99, 0
	v_mov_b32_e32 v0, 0
	v_mov_b32_e32 v1, v0
	v_mov_b32_e32 v2, v0
	v_mov_b32_e32 v3, v0
	v_mov_b32_e32 v4, v0
	v_mov_b32_e32 v5, v0
	v_mov_b32_e32 v6, v0
	v_mov_b32_e32 v7, v0
	v_mov_b32_e32 v8, v0
	v_mov_b32_e32 v9, v0
	v_mov_b32_e32 v10, v0
	v_mov_b32_e32 v11, v0
	v_mov_b32_e32 v12, v0
	v_mov_b32_e32 v13, v0
	v_mov_b32_e32 v14, v0
	v_mov_b32_e32 v15, v0
	v_mov_b32_e32 v16, v0
	v_mov_b32_e32 v17, v0
	v_mov_b32_e32 v18, v0
	v_mov_b32_e32 v19, v0
	v_mov_b32_e32 v20, v0
	v_mov_b32_e32 v21, v0
	v_mov_b32_e32 v22, v0
	v_mov_b32_e32 v23, v0
	v_mov_b32_e32 v24, v0
	v_mov_b32_e32 v25, v0
	v_mov_b32_e32 v26, v0
	v_mov_b32_e32 v27, v0
	v_mov_b32_e32 v28, v0
	v_mov_b32_e32 v29, v0
	v_mov_b32_e32 v30, v0
	v_mov_b32_e32 v31, v0
	v_mov_b32_e32 v32, v0
	v_mov_b32_e32 v33, v0
	v_mov_b32_e32 v34, v0
	v_mov_b32_e32 v35, v0
	v_mov_b32_e32 v36, v0
	v_mov_b32_e32 v37, v0
	v_mov_b32_e32 v38, v0
	v_mov_b32_e32 v39, v0
	v_mov_b32_e32 v40, v0
	v_mov_b32_e32 v41, v0
	v_mov_b32_e32 v42, v0
	v_mov_b32_e32 v43, v0
	v_mov_b32_e32 v44, v0
	v_mov_b32_e32 v45, v0
	v_mov_b32_e32 v46, v0
	v_mov_b32_e32 v47, v0
	v_mov_b32_e32 v48, v0
	v_mov_b32_e32 v49, v0
	v_mov_b32_e32 v50, v0
	v_mov_b32_e32 v51, v0
	v_mov_b32_e32 v52, v0
	v_mov_b32_e32 v53, v0
	v_mov_b32_e32 v54, v0
	v_mov_b32_e32 v55, v0
	v_mov_b32_e32 v56, v0
	v_mov_b32_e32 v57, v0
	v_mov_b32_e32 v58, v0
	v_mov_b32_e32 v59, v0
	v_mov_b32_e32 v60, v0
	v_mov_b32_e32 v61, v0
	v_mov_b32_e32 v62, v0
	v_mov_b32_e32 v63, v0
	v_mov_b32_e32 v64, v0
	v_mov_b32_e32 v65, v0
	v_mov_b32_e32 v66, v0
	v_mov_b32_e32 v67, v0
	v_mov_b32_e32 v68, v0
	v_mov_b32_e32 v69, v0
	v_mov_b32_e32 v70, v0
	v_mov_b32_e32 v71, v0
	v_mov_b32_e32 v72, v0
	v_mov_b32_e32 v73, v0
	v_mov_b32_e32 v74, v0
	v_mov_b32_e32 v75, v0
	v_mov_b32_e32 v76, v0
	v_mov_b32_e32 v77, v0
	v_mov_b32_e32 v78, v0
	v_mov_b32_e32 v79, v0
	v_mov_b32_e32 v80, v0
	v_mov_b32_e32 v81, v0
	v_mov_b32_e32 v82, v0
	v_mov_b32_e32 v83, v0
	v_mov_b32_e32 v84, v0
	v_mov_b32_e32 v85, v0
	v_mov_b32_e32 v86, v0
	v_mov_b32_e32 v87, v0
	v_mov_b32_e32 v88, v0
	v_mov_b32_e32 v89, v0
	v_mov_b32_e32 v90, v0
	v_mov_b32_e32 v91, v0
	v_mov_b32_e32 v92, v0
	v_mov_b32_e32 v93, v0
	v_mov_b32_e32 v94, v0
	v_mov_b32_e32 v95, v0
	v_mov_b32_e32 v96, v0
	v_mov_b32_e32 v97, v0
	v_mov_b32_e32 v98, v0
	v_mov_b32_e32 v99, v0
	v_mov_b32_e32 v100, v0
	v_mov_b32_e32 v101, v0
	v_mov_b32_e32 v102, v0
	v_mov_b32_e32 v103, v0
	v_mov_b32_e32 v104, v0
	v_mov_b32_e32 v105, v0
	v_mov_b32_e32 v106, v0
	v_mov_b32_e32 v107, v0
	v_mov_b32_e32 v108, v0
	v_mov_b32_e32 v109, v0
	v_mov_b32_e32 v110, v0
	v_mov_b32_e32 v111, v0
	v_mov_b32_e32 v112, v0
	v_mov_b32_e32 v113, v0
	v_mov_b32_e32 v114, v0
	v_mov_b32_e32 v115, v0
	v_mov_b32_e32 v116, v0
	v_mov_b32_e32 v117, v0
	v_mov_b32_e32 v118, v0
	v_mov_b32_e32 v119, v0
	v_mov_b32_e32 v120, v0
	v_mov_b32_e32 v121, v0
	v_mov_b32_e32 v122, v0
	v_mov_b32_e32 v123, v0
	v_mov_b32_e32 v124, v0
	v_mov_b32_e32 v125, v0
	v_mov_b32_e32 v126, v0
	v_mov_b32_e32 v127, v0
	s_mov_b32 s94, 0
.Lgp6a_loop:
	s_waitcnt vmcnt(0) lgkmcnt(0)
	s_barrier
	s_add_u32 m0, s96, 0x4000
	s_nop 0
	global_load_lds_dwordx4 v232, s[90:91]
	s_add_u32 m0, s96, 0x5000
	s_nop 0
	global_load_lds_dwordx4 v233, s[90:91]
	s_add_u32 m0, s96, 0x6000
	s_nop 0
	global_load_lds_dwordx4 v234, s[90:91]
	s_add_u32 m0, s96, 0x7000
	s_nop 0
	global_load_lds_dwordx4 v235, s[90:91]
	s_add_u32 s90, s90, 0x80
	s_addc_u32 s91, s91, 0
	ds_read_b128 v[164:167], v238 offset:32768
	ds_read_b128 v[172:175], v238 offset:34816
	ds_read_b128 v[176:179], v238 offset:36864
	ds_read_b128 v[180:183], v238 offset:38912
	ds_read_b128 v[200:203], v238 offset:49152
	ds_read_b128 v[204:207], v238 offset:51200
	ds_read_b128 v[208:211], v238 offset:53248
	ds_read_b128 v[212:215], v238 offset:55296
	ds_read_b128 v[184:187], v240 offset:32768
	ds_read_b128 v[188:191], v240 offset:34816
	ds_read_b128 v[192:195], v240 offset:36864
	ds_read_b128 v[196:199], v240 offset:38912
	ds_read_b128 v[216:219], v240 offset:49152
	ds_read_b128 v[220:223], v240 offset:51200
	ds_read_b128 v[224:227], v240 offset:53248
	ds_read_b128 v[228:231], v240 offset:55296
	ds_read_b128 v[128:131], v239
	ds_read_b128 v[132:135], v239 offset:2048
	ds_read_b128 v[136:139], v239 offset:4096
	ds_read_b128 v[140:143], v239 offset:6144
	s_waitcnt lgkmcnt(0)
	s_barrier
	ds_read_b128 v[148:151], v241
	ds_read_b128 v[152:155], v241 offset:2048
	ds_read_b128 v[156:159], v241 offset:4096
	ds_read_b128 v[160:163], v241 offset:6144
	s_add_u32 m0, s96, 0x8000
	v_mfma_f32_16x16x32_bf16 v[0:3], v[128:131], v[164:167], v[0:3]
	global_load_lds_dwordx4 v232, s[92:93]
	v_mfma_f32_16x16x32_bf16 v[64:67], v[128:131], v[200:203], v[64:67]
	s_add_u32 m0, s96, 0x9000
	v_mfma_f32_16x16x32_bf16 v[4:7], v[132:135], v[164:167], v[4:7]
	global_load_lds_dwordx4 v233, s[92:93]
	v_mfma_f32_16x16x32_bf16 v[68:71], v[132:135], v[200:203], v[68:71]
	s_add_u32 m0, s96, 0xa000
	v_mfma_f32_16x16x32_bf16 v[8:11], v[136:139], v[164:167], v[8:11]
	global_load_lds_dwordx4 v234, s[92:93]
	v_mfma_f32_16x16x32_bf16 v[72:75], v[136:139], v[200:203], v[72:75]
	s_add_u32 m0, s96, 0xb000
	v_mfma_f32_16x16x32_bf16 v[12:15], v[140:143], v[164:167], v[12:15]
	global_load_lds_dwordx4 v235, s[92:93]
	v_mfma_f32_16x16x32_bf16 v[76:79], v[140:143], v[200:203], v[76:79]
	s_add_u32 m0, s96, 0xc000
	v_mfma_f32_16x16x32_bf16 v[16:19], v[128:131], v[172:175], v[16:19]
	global_load_lds_dwordx4 v232, s[98:99]
	v_mfma_f32_16x16x32_bf16 v[80:83], v[128:131], v[204:207], v[80:83]
	s_add_u32 m0, s96, 0xd000
	v_mfma_f32_16x16x32_bf16 v[20:23], v[132:135], v[172:175], v[20:23]
	global_load_lds_dwordx4 v233, s[98:99]
	v_mfma_f32_16x16x32_bf16 v[84:87], v[132:135], v[204:207], v[84:87]
	s_add_u32 m0, s96, 0xe000
	v_mfma_f32_16x16x32_bf16 v[24:27], v[136:139], v[172:175], v[24:27]
	global_load_lds_dwordx4 v234, s[98:99]
	v_mfma_f32_16x16x32_bf16 v[88:91], v[136:139], v[204:207], v[88:91]
	s_add_u32 m0, s96, 0xf000
	v_mfma_f32_16x16x32_bf16 v[28:31], v[140:143], v[172:175], v[28:31]
	global_load_lds_dwordx4 v235, s[98:99]
	s_add_u32 s92, s92, 0x80
	s_addc_u32 s93, s93, 0
	s_add_u32 s98, s98, 0x80
	s_addc_u32 s99, s99, 0
	v_mfma_f32_16x16x32_bf16 v[92:95], v[140:143], v[204:207], v[92:95]
	v_mfma_f32_16x16x32_bf16 v[32:35], v[128:131], v[176:179], v[32:35]
	v_mfma_f32_16x16x32_bf16 v[96:99], v[128:131], v[208:211], v[96:99]
	v_mfma_f32_16x16x32_bf16 v[36:39], v[132:135], v[176:179], v[36:39]
	v_mfma_f32_16x16x32_bf16 v[100:103], v[132:135], v[208:211], v[100:103]
	v_mfma_f32_16x16x32_bf16 v[40:43], v[136:139], v[176:179], v[40:43]
	v_mfma_f32_16x16x32_bf16 v[104:107], v[136:139], v[208:211], v[104:107]
	v_mfma_f32_16x16x32_bf16 v[44:47], v[140:143], v[176:179], v[44:47]
	v_mfma_f32_16x16x32_bf16 v[108:111], v[140:143], v[208:211], v[108:111]
	v_mfma_f32_16x16x32_bf16 v[48:51], v[128:131], v[180:183], v[48:51]
	v_mfma_f32_16x16x32_bf16 v[112:115], v[128:131], v[212:215], v[112:115]
	v_mfma_f32_16x16x32_bf16 v[52:55], v[132:135], v[180:183], v[52:55]
	v_mfma_f32_16x16x32_bf16 v[116:119], v[132:135], v[212:215], v[116:119]
	v_mfma_f32_16x16x32_bf16 v[56:59], v[136:139], v[180:183], v[56:59]
	v_mfma_f32_16x16x32_bf16 v[120:123], v[136:139], v[212:215], v[120:123]
	v_mfma_f32_16x16x32_bf16 v[60:63], v[140:143], v[180:183], v[60:63]
	v_mfma_f32_16x16x32_bf16 v[124:127], v[140:143], v[212:215], v[124:127]
	s_waitcnt lgkmcnt(0)
	v_mfma_f32_16x16x32_bf16 v[0:3], v[148:151], v[184:187], v[0:3]
	v_mfma_f32_16x16x32_bf16 v[64:67], v[148:151], v[216:219], v[64:67]
	v_mfma_f32_16x16x32_bf16 v[4:7], v[152:155], v[184:187], v[4:7]
	v_mfma_f32_16x16x32_bf16 v[68:71], v[152:155], v[216:219], v[68:71]
	v_mfma_f32_16x16x32_bf16 v[8:11], v[156:159], v[184:187], v[8:11]
	v_mfma_f32_16x16x32_bf16 v[72:75], v[156:159], v[216:219], v[72:75]
	v_mfma_f32_16x16x32_bf16 v[12:15], v[160:163], v[184:187], v[12:15]
	v_mfma_f32_16x16x32_bf16 v[76:79], v[160:163], v[216:219], v[76:79]
	v_mfma_f32_16x16x32_bf16 v[16:19], v[148:151], v[188:191], v[16:19]
	v_mfma_f32_16x16x32_bf16 v[80:83], v[148:151], v[220:223], v[80:83]
	v_mfma_f32_16x16x32_bf16 v[20:23], v[152:155], v[188:191], v[20:23]
	v_mfma_f32_16x16x32_bf16 v[84:87], v[152:155], v[220:223], v[84:87]
	v_mfma_f32_16x16x32_bf16 v[24:27], v[156:159], v[188:191], v[24:27]
	v_mfma_f32_16x16x32_bf16 v[88:91], v[156:159], v[220:223], v[88:91]
	v_mfma_f32_16x16x32_bf16 v[28:31], v[160:163], v[188:191], v[28:31]
	v_mfma_f32_16x16x32_bf16 v[92:95], v[160:163], v[220:223], v[92:95]
	v_mfma_f32_16x16x32_bf16 v[32:35], v[148:151], v[192:195], v[32:35]
	v_mfma_f32_16x16x32_bf16 v[96:99], v[148:151], v[224:227], v[96:99]
	v_mfma_f32_16x16x32_bf16 v[36:39], v[152:155], v[192:195], v[36:39]
	v_mfma_f32_16x16x32_bf16 v[100:103], v[152:155], v[224:227], v[100:103]
	v_mfma_f32_16x16x32_bf16 v[40:43], v[156:159], v[192:195], v[40:43]
	v_mfma_f32_16x16x32_bf16 v[104:107], v[156:159], v[224:227], v[104:107]
	v_mfma_f32_16x16x32_bf16 v[44:47], v[160:163], v[192:195], v[44:47]
	v_mfma_f32_16x16x32_bf16 v[108:111], v[160:163], v[224:227], v[108:111]
	v_mfma_f32_16x16x32_bf16 v[48:51], v[148:151], v[196:199], v[48:51]
	v_mfma_f32_16x16x32_bf16 v[112:115], v[148:151], v[228:231], v[112:115]
	v_mfma_f32_16x16x32_bf16 v[52:55], v[152:155], v[196:199], v[52:55]
	v_mfma_f32_16x16x32_bf16 v[116:119], v[152:155], v[228:231], v[116:119]
	v_mfma_f32_16x16x32_bf16 v[56:59], v[156:159], v[196:199], v[56:59]
	v_mfma_f32_16x16x32_bf16 v[120:123], v[156:159], v[228:231], v[120:123]
	v_mfma_f32_16x16x32_bf16 v[60:63], v[160:163], v[196:199], v[60:63]
	v_mfma_f32_16x16x32_bf16 v[124:127], v[160:163], v[228:231], v[124:127]
	s_waitcnt vmcnt(0) lgkmcnt(0)
	s_barrier
	s_cmp_eq_u32 s94, 7
	s_cbranch_scc1 .Lgp6a_noS
	s_add_u32 m0, s96, 0x0
	s_nop 0
	global_load_lds_dwordx4 v232, s[90:91]
	s_add_u32 m0, s96, 0x1000
	s_nop 0
	global_load_lds_dwordx4 v233, s[90:91]
	s_add_u32 m0, s96, 0x2000
	s_nop 0
	global_load_lds_dwordx4 v234, s[90:91]
	s_add_u32 m0, s96, 0x3000
	s_nop 0
	global_load_lds_dwordx4 v235, s[90:91]
	s_add_u32 s90, s90, 0x80
	s_addc_u32 s91, s91, 0
.Lgp6a_noS:
	ds_read_b128 v[164:167], v238 offset:32768
	ds_read_b128 v[172:175], v238 offset:34816
	ds_read_b128 v[176:179], v238 offset:36864
	ds_read_b128 v[180:183], v238 offset:38912
	ds_read_b128 v[200:203], v238 offset:49152
	ds_read_b128 v[204:207], v238 offset:51200
	ds_read_b128 v[208:211], v238 offset:53248
	ds_read_b128 v[212:215], v238 offset:55296
	ds_read_b128 v[184:187], v240 offset:32768
	ds_read_b128 v[188:191], v240 offset:34816
	ds_read_b128 v[192:195], v240 offset:36864
	ds_read_b128 v[196:199], v240 offset:38912
	ds_read_b128 v[216:219], v240 offset:49152
	ds_read_b128 v[220:223], v240 offset:51200
	ds_read_b128 v[224:227], v240 offset:53248
	ds_read_b128 v[228:231], v240 offset:55296
	ds_read_b128 v[128:131], v239 offset:16384
	ds_read_b128 v[132:135], v239 offset:18432
	ds_read_b128 v[136:139], v239 offset:20480
	ds_read_b128 v[140:143], v239 offset:22528
	s_waitcnt lgkmcnt(0)
	s_barrier
	ds_read_b128 v[148:151], v241 offset:16384
	ds_read_b128 v[152:155], v241 offset:18432
	ds_read_b128 v[156:159], v241 offset:20480
	ds_read_b128 v[160:163], v241 offset:22528
	s_cmp_eq_u32 s94, 7
	s_cbranch_scc1 .Lgp6a_last
	s_add_u32 m0, s96, 0x8000
	v_mfma_f32_16x16x32_bf16 v[0:3], v[128:131], v[164:167], v[0:3]
	global_load_lds_dwordx4 v232, s[92:93]
	v_mfma_f32_16x16x32_bf16 v[64:67], v[128:131], v[200:203], v[64:67]
	s_add_u32 m0, s96, 0x9000
	v_mfma_f32_16x16x32_bf16 v[4:7], v[132:135], v[164:167], v[4:7]
	global_load_lds_dwordx4 v233, s[92:93]
	v_mfma_f32_16x16x32_bf16 v[68:71], v[132:135], v[200:203], v[68:71]
	s_add_u32 m0, s96, 0xa000
	v_mfma_f32_16x16x32_bf16 v[8:11], v[136:139], v[164:167], v[8:11]
	global_load_lds_dwordx4 v234, s[92:93]
	v_mfma_f32_16x16x32_bf16 v[72:75], v[136:139], v[200:203], v[72:75]
	s_add_u32 m0, s96, 0xb000
	v_mfma_f32_16x16x32_bf16 v[12:15], v[140:143], v[164:167], v[12:15]
	global_load_lds_dwordx4 v235, s[92:93]
	v_mfma_f32_16x16x32_bf16 v[76:79], v[140:143], v[200:203], v[76:79]
	s_add_u32 m0, s96, 0xc000
	v_mfma_f32_16x16x32_bf16 v[16:19], v[128:131], v[172:175], v[16:19]
	global_load_lds_dwordx4 v232, s[98:99]
	v_mfma_f32_16x16x32_bf16 v[80:83], v[128:131], v[204:207], v[80:83]
	s_add_u32 m0, s96, 0xd000
	v_mfma_f32_16x16x32_bf16 v[20:23], v[132:135], v[172:175], v[20:23]
	global_load_lds_dwordx4 v233, s[98:99]
	v_mfma_f32_16x16x32_bf16 v[84:87], v[132:135], v[204:207], v[84:87]
	s_add_u32 m0, s96, 0xe000
	v_mfma_f32_16x16x32_bf16 v[24:27], v[136:139], v[172:175], v[24:27]
	global_load_lds_dwordx4 v234, s[98:99]
	v_mfma_f32_16x16x32_bf16 v[88:91], v[136:139], v[204:207], v[88:91]
	s_add_u32 m0, s96, 0xf000
	v_mfma_f32_16x16x32_bf16 v[28:31], v[140:143], v[172:175], v[28:31]
	global_load_lds_dwordx4 v235, s[98:99]
	s_add_u32 s92, s92, 0x80
	s_addc_u32 s93, s93, 0
	s_add_u32 s98, s98, 0x80
	s_addc_u32 s99, s99, 0
	v_mfma_f32_16x16x32_bf16 v[92:95], v[140:143], v[204:207], v[92:95]
	v_mfma_f32_16x16x32_bf16 v[32:35], v[128:131], v[176:179], v[32:35]
	v_mfma_f32_16x16x32_bf16 v[96:99], v[128:131], v[208:211], v[96:99]
	v_mfma_f32_16x16x32_bf16 v[36:39], v[132:135], v[176:179], v[36:39]
	v_mfma_f32_16x16x32_bf16 v[100:103], v[132:135], v[208:211], v[100:103]
	v_mfma_f32_16x16x32_bf16 v[40:43], v[136:139], v[176:179], v[40:43]
	v_mfma_f32_16x16x32_bf16 v[104:107], v[136:139], v[208:211], v[104:107]
	v_mfma_f32_16x16x32_bf16 v[44:47], v[140:143], v[176:179], v[44:47]
	v_mfma_f32_16x16x32_bf16 v[108:111], v[140:143], v[208:211], v[108:111]
	v_mfma_f32_16x16x32_bf16 v[48:51], v[128:131], v[180:183], v[48:51]
	v_mfma_f32_16x16x32_bf16 v[112:115], v[128:131], v[212:215], v[112:115]
	v_mfma_f32_16x16x32_bf16 v[52:55], v[132:135], v[180:183], v[52:55]
	v_mfma_f32_16x16x32_bf16 v[116:119], v[132:135], v[212:215], v[116:119]
	v_mfma_f32_16x16x32_bf16 v[56:59], v[136:139], v[180:183], v[56:59]
	v_mfma_f32_16x16x32_bf16 v[120:123], v[136:139], v[212:215], v[120:123]
	v_mfma_f32_16x16x32_bf16 v[60:63], v[140:143], v[180:183], v[60:63]
	v_mfma_f32_16x16x32_bf16 v[124:127], v[140:143], v[212:215], v[124:127]
	s_waitcnt lgkmcnt(0)
	v_mfma_f32_16x16x32_bf16 v[0:3], v[148:151], v[184:187], v[0:3]
	v_mfma_f32_16x16x32_bf16 v[64:67], v[148:151], v[216:219], v[64:67]
	v_mfma_f32_16x16x32_bf16 v[4:7], v[152:155], v[184:187], v[4:7]
	v_mfma_f32_16x16x32_bf16 v[68:71], v[152:155], v[216:219], v[68:71]
	v_mfma_f32_16x16x32_bf16 v[8:11], v[156:159], v[184:187], v[8:11]
	v_mfma_f32_16x16x32_bf16 v[72:75], v[156:159], v[216:219], v[72:75]
	v_mfma_f32_16x16x32_bf16 v[12:15], v[160:163], v[184:187], v[12:15]
	v_mfma_f32_16x16x32_bf16 v[76:79], v[160:163], v[216:219], v[76:79]
	v_mfma_f32_16x16x32_bf16 v[16:19], v[148:151], v[188:191], v[16:19]
	v_mfma_f32_16x16x32_bf16 v[80:83], v[148:151], v[220:223], v[80:83]
	v_mfma_f32_16x16x32_bf16 v[20:23], v[152:155], v[188:191], v[20:23]
	v_mfma_f32_16x16x32_bf16 v[84:87], v[152:155], v[220:223], v[84:87]
	v_mfma_f32_16x16x32_bf16 v[24:27], v[156:159], v[188:191], v[24:27]
	v_mfma_f32_16x16x32_bf16 v[88:91], v[156:159], v[220:223], v[88:91]
	v_mfma_f32_16x16x32_bf16 v[28:31], v[160:163], v[188:191], v[28:31]
	v_mfma_f32_16x16x32_bf16 v[92:95], v[160:163], v[220:223], v[92:95]
	v_mfma_f32_16x16x32_bf16 v[32:35], v[148:151], v[192:195], v[32:35]
	v_mfma_f32_16x16x32_bf16 v[96:99], v[148:151], v[224:227], v[96:99]
	v_mfma_f32_16x16x32_bf16 v[36:39], v[152:155], v[192:195], v[36:39]
	v_mfma_f32_16x16x32_bf16 v[100:103], v[152:155], v[224:227], v[100:103]
	v_mfma_f32_16x16x32_bf16 v[40:43], v[156:159], v[192:195], v[40:43]
	v_mfma_f32_16x16x32_bf16 v[104:107], v[156:159], v[224:227], v[104:107]
	v_mfma_f32_16x16x32_bf16 v[44:47], v[160:163], v[192:195], v[44:47]
	v_mfma_f32_16x16x32_bf16 v[108:111], v[160:163], v[224:227], v[108:111]
	v_mfma_f32_16x16x32_bf16 v[48:51], v[148:151], v[196:199], v[48:51]
	v_mfma_f32_16x16x32_bf16 v[112:115], v[148:151], v[228:231], v[112:115]
	v_mfma_f32_16x16x32_bf16 v[52:55], v[152:155], v[196:199], v[52:55]
	v_mfma_f32_16x16x32_bf16 v[116:119], v[152:155], v[228:231], v[116:119]
	v_mfma_f32_16x16x32_bf16 v[56:59], v[156:159], v[196:199], v[56:59]
	v_mfma_f32_16x16x32_bf16 v[120:123], v[156:159], v[228:231], v[120:123]
	v_mfma_f32_16x16x32_bf16 v[60:63], v[160:163], v[196:199], v[60:63]
	v_mfma_f32_16x16x32_bf16 v[124:127], v[160:163], v[228:231], v[124:127]
	s_add_u32 s94, s94, 1
	s_branch .Lgp6a_loop
.Lgp6a_last:
	v_mfma_f32_16x16x32_bf16 v[0:3], v[128:131], v[164:167], v[0:3]
	v_mfma_f32_16x16x32_bf16 v[64:67], v[128:131], v[200:203], v[64:67]
	v_mfma_f32_16x16x32_bf16 v[4:7], v[132:135], v[164:167], v[4:7]
	v_mfma_f32_16x16x32_bf16 v[68:71], v[132:135], v[200:203], v[68:71]
	v_mfma_f32_16x16x32_bf16 v[8:11], v[136:139], v[164:167], v[8:11]
	v_mfma_f32_16x16x32_bf16 v[72:75], v[136:139], v[200:203], v[72:75]
	v_mfma_f32_16x16x32_bf16 v[12:15], v[140:143], v[164:167], v[12:15]
	v_mfma_f32_16x16x32_bf16 v[76:79], v[140:143], v[200:203], v[76:79]
	v_mfma_f32_16x16x32_bf16 v[16:19], v[128:131], v[172:175], v[16:19]
	v_mfma_f32_16x16x32_bf16 v[80:83], v[128:131], v[204:207], v[80:83]
	v_mfma_f32_16x16x32_bf16 v[20:23], v[132:135], v[172:175], v[20:23]
	v_mfma_f32_16x16x32_bf16 v[84:87], v[132:135], v[204:207], v[84:87]
	v_mfma_f32_16x16x32_bf16 v[24:27], v[136:139], v[172:175], v[24:27]
	v_mfma_f32_16x16x32_bf16 v[88:91], v[136:139], v[204:207], v[88:91]
	v_mfma_f32_16x16x32_bf16 v[28:31], v[140:143], v[172:175], v[28:31]
	v_mfma_f32_16x16x32_bf16 v[92:95], v[140:143], v[204:207], v[92:95]
	v_mfma_f32_16x16x32_bf16 v[32:35], v[128:131], v[176:179], v[32:35]
	v_mfma_f32_16x16x32_bf16 v[96:99], v[128:131], v[208:211], v[96:99]
	v_mfma_f32_16x16x32_bf16 v[36:39], v[132:135], v[176:179], v[36:39]
	v_mfma_f32_16x16x32_bf16 v[100:103], v[132:135], v[208:211], v[100:103]
	v_mfma_f32_16x16x32_bf16 v[40:43], v[136:139], v[176:179], v[40:43]
	v_mfma_f32_16x16x32_bf16 v[104:107], v[136:139], v[208:211], v[104:107]
	v_mfma_f32_16x16x32_bf16 v[44:47], v[140:143], v[176:179], v[44:47]
	v_mfma_f32_16x16x32_bf16 v[108:111], v[140:143], v[208:211], v[108:111]
	v_mfma_f32_16x16x32_bf16 v[48:51], v[128:131], v[180:183], v[48:51]
	v_mfma_f32_16x16x32_bf16 v[112:115], v[128:131], v[212:215], v[112:115]
	v_mfma_f32_16x16x32_bf16 v[52:55], v[132:135], v[180:183], v[52:55]
	v_mfma_f32_16x16x32_bf16 v[116:119], v[132:135], v[212:215], v[116:119]
	v_mfma_f32_16x16x32_bf16 v[56:59], v[136:139], v[180:183], v[56:59]
	v_mfma_f32_16x16x32_bf16 v[120:123], v[136:139], v[212:215], v[120:123]
	v_mfma_f32_16x16x32_bf16 v[60:63], v[140:143], v[180:183], v[60:63]
	v_mfma_f32_16x16x32_bf16 v[124:127], v[140:143], v[212:215], v[124:127]
	s_waitcnt lgkmcnt(0)
	v_mfma_f32_16x16x32_bf16 v[0:3], v[148:151], v[184:187], v[0:3]
	v_mfma_f32_16x16x32_bf16 v[64:67], v[148:151], v[216:219], v[64:67]
	v_mfma_f32_16x16x32_bf16 v[4:7], v[152:155], v[184:187], v[4:7]
	v_mfma_f32_16x16x32_bf16 v[68:71], v[152:155], v[216:219], v[68:71]
	v_mfma_f32_16x16x32_bf16 v[8:11], v[156:159], v[184:187], v[8:11]
	v_mfma_f32_16x16x32_bf16 v[72:75], v[156:159], v[216:219], v[72:75]
	v_mfma_f32_16x16x32_bf16 v[12:15], v[160:163], v[184:187], v[12:15]
	v_mfma_f32_16x16x32_bf16 v[76:79], v[160:163], v[216:219], v[76:79]
	v_mfma_f32_16x16x32_bf16 v[16:19], v[148:151], v[188:191], v[16:19]
	v_mfma_f32_16x16x32_bf16 v[80:83], v[148:151], v[220:223], v[80:83]
	v_mfma_f32_16x16x32_bf16 v[20:23], v[152:155], v[188:191], v[20:23]
	v_mfma_f32_16x16x32_bf16 v[84:87], v[152:155], v[220:223], v[84:87]
	v_mfma_f32_16x16x32_bf16 v[24:27], v[156:159], v[188:191], v[24:27]
	v_mfma_f32_16x16x32_bf16 v[88:91], v[156:159], v[220:223], v[88:91]
	v_mfma_f32_16x16x32_bf16 v[28:31], v[160:163], v[188:191], v[28:31]
	v_mfma_f32_16x16x32_bf16 v[92:95], v[160:163], v[220:223], v[92:95]
	v_mfma_f32_16x16x32_bf16 v[32:35], v[148:151], v[192:195], v[32:35]
	v_mfma_f32_16x16x32_bf16 v[96:99], v[148:151], v[224:227], v[96:99]
	v_mfma_f32_16x16x32_bf16 v[36:39], v[152:155], v[192:195], v[36:39]
	v_mfma_f32_16x16x32_bf16 v[100:103], v[152:155], v[224:227], v[100:103]
	v_mfma_f32_16x16x32_bf16 v[40:43], v[156:159], v[192:195], v[40:43]
	v_mfma_f32_16x16x32_bf16 v[104:107], v[156:159], v[224:227], v[104:107]
	v_mfma_f32_16x16x32_bf16 v[44:47], v[160:163], v[192:195], v[44:47]
	v_mfma_f32_16x16x32_bf16 v[108:111], v[160:163], v[224:227], v[108:111]
	v_mfma_f32_16x16x32_bf16 v[48:51], v[148:151], v[196:199], v[48:51]
	v_mfma_f32_16x16x32_bf16 v[112:115], v[148:151], v[228:231], v[112:115]
	v_mfma_f32_16x16x32_bf16 v[52:55], v[152:155], v[196:199], v[52:55]
	v_mfma_f32_16x16x32_bf16 v[116:119], v[152:155], v[228:231], v[116:119]
	v_mfma_f32_16x16x32_bf16 v[56:59], v[156:159], v[196:199], v[56:59]
	v_mfma_f32_16x16x32_bf16 v[120:123], v[156:159], v[228:231], v[120:123]
	v_mfma_f32_16x16x32_bf16 v[60:63], v[160:163], v[196:199], v[60:63]
	v_mfma_f32_16x16x32_bf16 v[124:127], v[160:163], v[228:231], v[124:127]
	s_nop 7
	s_nop 3
	s_mov_b32 s83, 0

.Lp6a_epdone:
	v_lshrrev_b32_e32 v236, 3, v168
	v_lshrrev_b32_e32 v237, 4, v168
	v_xor_b32_e32 v237, v237, v168
	v_and_b32_e32 v237, 7, v237
	v_lshlrev_b32_e32 v237, 4, v237
	v_lshl_or_b32 v232, v236, 11, v237
	v_add_u32_e32 v233, 0x10000, v232
	v_add_u32_e32 v234, 0x20000, v232
	v_add_u32_e32 v235, 0x30000, v232
	s_load_dwordx2 s[90:91], s[0:1], 0xa0
	s_load_dwordx2 s[92:93], s[0:1], 0xb0
	v_lshrrev_b32_e32 v237, 6, v168
	s_nop 1
	v_readfirstlane_b32 s97, v237
	s_nop 3
	s_lshl_b32 s96, s97, 10
	s_add_u32 s96, s96, 16
	s_add_u32 s94, s81, s80
	s_cmp_lt_i32 s94, s82
	s_cselect_b32 s95, 1, 0
	s_cmp_lg_u64 s[20:21], 0
	s_cselect_b32 s95, 0, s95
	s_cmp_ge_u32 s94, 0x40
	s_cselect_b32 s97, 1, 0
	s_mul_i32 s100, s97, 0x40
	s_sub_u32 s100, s94, s100
	s_lshr_b32 s101, s100, 3
	s_and_b32 s100, s100, 7
	s_lshl_b32 s97, s97, 3
	s_add_u32 s100, s100, s97
	s_add_u32 s100, s100, s79
	s_cmp_lg_u32 s101, s74
	s_cselect_b32 s95, 0, s95
	s_cmp_eq_u32 s95, 1
	s_cselect_b32 s101, s100, s70
	s_mov_b32 s97, s101
	s_waitcnt lgkmcnt(0)
	s_lshl_b32 s94, s74, 18
	s_add_u32 s98, s92, s94
	s_addc_u32 s99, s93, 0
	s_lshl_b32 s101, s101, 18
	s_add_u32 s101, s101, 0x2000000
	s_add_u32 s92, s90, s101
	s_addc_u32 s93, s91, 0
	s_lshl_b32 s94, s70, 18
	s_add_u32 s94, s94, 0x2000000
	s_add_u32 s90, s90, s94
	s_addc_u32 s91, s91, 0
	s_mov_b64 s[100:101], s[90:91]
	s_mov_b64 s[90:91], s[98:99]
	s_mov_b64 s[98:99], s[92:93]
	s_mov_b64 s[92:93], s[100:101]
	s_waitcnt vmcnt(0)
	s_barrier
	s_add_u32 m0, s96, 0x0
	s_nop 0
	global_load_lds_dwordx4 v232, s[90:91]
	s_add_u32 m0, s96, 0x1000
	s_nop 0
	global_load_lds_dwordx4 v233, s[90:91]
	s_add_u32 m0, s96, 0x2000
	s_nop 0
	global_load_lds_dwordx4 v234, s[90:91]
	s_add_u32 m0, s96, 0x3000
	s_nop 0
	global_load_lds_dwordx4 v235, s[90:91]
	s_add_u32 m0, s96, 0x8000
	s_nop 0
	global_load_lds_dwordx4 v232, s[92:93]
	s_add_u32 m0, s96, 0x9000
	s_nop 0
	global_load_lds_dwordx4 v233, s[92:93]
	s_add_u32 m0, s96, 0xa000
	s_nop 0
	global_load_lds_dwordx4 v234, s[92:93]
	s_add_u32 m0, s96, 0xb000
	s_nop 0
	global_load_lds_dwordx4 v235, s[92:93]
	s_add_u32 m0, s96, 0xc000
	s_nop 0
	global_load_lds_dwordx4 v232, s[98:99]
	s_add_u32 m0, s96, 0xd000
	s_nop 0
	global_load_lds_dwordx4 v233, s[98:99]
	s_add_u32 m0, s96, 0xe000
	s_nop 0
	global_load_lds_dwordx4 v234, s[98:99]
	s_add_u32 m0, s96, 0xf000
	s_nop 0
	global_load_lds_dwordx4 v235, s[98:99]
	s_add_u32 s90, s90, 0x80
	s_addc_u32 s91, s91, 0
	s_add_u32 s92, s92, 0x80
	s_addc_u32 s93, s93, 0
	s_add_u32 s98, s98, 0x80
	s_addc_u32 s99, s99, 0
	v_mov_b32_e32 v0, 0
	v_mov_b32_e32 v1, v0
	v_mov_b32_e32 v2, v0
	v_mov_b32_e32 v3, v0
	v_mov_b32_e32 v4, v0
	v_mov_b32_e32 v5, v0
	v_mov_b32_e32 v6, v0
	v_mov_b32_e32 v7, v0
	v_mov_b32_e32 v8, v0
	v_mov_b32_e32 v9, v0
	v_mov_b32_e32 v10, v0
	v_mov_b32_e32 v11, v0
	v_mov_b32_e32 v12, v0
	v_mov_b32_e32 v13, v0
	v_mov_b32_e32 v14, v0
	v_mov_b32_e32 v15, v0
	v_mov_b32_e32 v16, v0
	v_mov_b32_e32 v17, v0
	v_mov_b32_e32 v18, v0
	v_mov_b32_e32 v19, v0
	v_mov_b32_e32 v20, v0
	v_mov_b32_e32 v21, v0
	v_mov_b32_e32 v22, v0
	v_mov_b32_e32 v23, v0
	v_mov_b32_e32 v24, v0
	v_mov_b32_e32 v25, v0
	v_mov_b32_e32 v26, v0
	v_mov_b32_e32 v27, v0
	v_mov_b32_e32 v28, v0
	v_mov_b32_e32 v29, v0
	v_mov_b32_e32 v30, v0
	v_mov_b32_e32 v31, v0
	v_mov_b32_e32 v32, v0
	v_mov_b32_e32 v33, v0
	v_mov_b32_e32 v34, v0
	v_mov_b32_e32 v35, v0
	v_mov_b32_e32 v36, v0
	v_mov_b32_e32 v37, v0
	v_mov_b32_e32 v38, v0
	v_mov_b32_e32 v39, v0
	v_mov_b32_e32 v40, v0
	v_mov_b32_e32 v41, v0
	v_mov_b32_e32 v42, v0
	v_mov_b32_e32 v43, v0
	v_mov_b32_e32 v44, v0
	v_mov_b32_e32 v45, v0
	v_mov_b32_e32 v46, v0
	v_mov_b32_e32 v47, v0
	v_mov_b32_e32 v48, v0
	v_mov_b32_e32 v49, v0
	v_mov_b32_e32 v50, v0
	v_mov_b32_e32 v51, v0
	v_mov_b32_e32 v52, v0
	v_mov_b32_e32 v53, v0
	v_mov_b32_e32 v54, v0
	v_mov_b32_e32 v55, v0
	v_mov_b32_e32 v56, v0
	v_mov_b32_e32 v57, v0
	v_mov_b32_e32 v58, v0
	v_mov_b32_e32 v59, v0
	v_mov_b32_e32 v60, v0
	v_mov_b32_e32 v61, v0
	v_mov_b32_e32 v62, v0
	v_mov_b32_e32 v63, v0
	v_mov_b32_e32 v64, v0
	v_mov_b32_e32 v65, v0
	v_mov_b32_e32 v66, v0
	v_mov_b32_e32 v67, v0
	v_mov_b32_e32 v68, v0
	v_mov_b32_e32 v69, v0
	v_mov_b32_e32 v70, v0
	v_mov_b32_e32 v71, v0
	v_mov_b32_e32 v72, v0
	v_mov_b32_e32 v73, v0
	v_mov_b32_e32 v74, v0
	v_mov_b32_e32 v75, v0
	v_mov_b32_e32 v76, v0
	v_mov_b32_e32 v77, v0
	v_mov_b32_e32 v78, v0
	v_mov_b32_e32 v79, v0
	v_mov_b32_e32 v80, v0
	v_mov_b32_e32 v81, v0
	v_mov_b32_e32 v82, v0
	v_mov_b32_e32 v83, v0
	v_mov_b32_e32 v84, v0
	v_mov_b32_e32 v85, v0
	v_mov_b32_e32 v86, v0
	v_mov_b32_e32 v87, v0
	v_mov_b32_e32 v88, v0
	v_mov_b32_e32 v89, v0
	v_mov_b32_e32 v90, v0
	v_mov_b32_e32 v91, v0
	v_mov_b32_e32 v92, v0
	v_mov_b32_e32 v93, v0
	v_mov_b32_e32 v94, v0
	v_mov_b32_e32 v95, v0
	v_mov_b32_e32 v96, v0
	v_mov_b32_e32 v97, v0
	v_mov_b32_e32 v98, v0
	v_mov_b32_e32 v99, v0
	v_mov_b32_e32 v100, v0
	v_mov_b32_e32 v101, v0
	v_mov_b32_e32 v102, v0
	v_mov_b32_e32 v103, v0
	v_mov_b32_e32 v104, v0
	v_mov_b32_e32 v105, v0
	v_mov_b32_e32 v106, v0
	v_mov_b32_e32 v107, v0
	v_mov_b32_e32 v108, v0
	v_mov_b32_e32 v109, v0
	v_mov_b32_e32 v110, v0
	v_mov_b32_e32 v111, v0
	v_mov_b32_e32 v112, v0
	v_mov_b32_e32 v113, v0
	v_mov_b32_e32 v114, v0
	v_mov_b32_e32 v115, v0
	v_mov_b32_e32 v116, v0
	v_mov_b32_e32 v117, v0
	v_mov_b32_e32 v118, v0
	v_mov_b32_e32 v119, v0
	v_mov_b32_e32 v120, v0
	v_mov_b32_e32 v121, v0
	v_mov_b32_e32 v122, v0
	v_mov_b32_e32 v123, v0
	v_mov_b32_e32 v124, v0
	v_mov_b32_e32 v125, v0
	v_mov_b32_e32 v126, v0
	v_mov_b32_e32 v127, v0
	s_mov_b32 s94, 0

.Lp6b_epdone:
	v_lshrrev_b32_e32 v236, 3, v168
	v_lshrrev_b32_e32 v237, 4, v168
	v_xor_b32_e32 v237, v237, v168
	v_and_b32_e32 v237, 7, v237
	v_lshlrev_b32_e32 v237, 4, v237
	v_lshl_or_b32 v232, v236, 11, v237
	v_add_u32_e32 v233, 0x10000, v232
	v_add_u32_e32 v234, 0x20000, v232
	v_add_u32_e32 v235, 0x30000, v232
	s_load_dwordx2 s[90:91], s[0:1], 0x100
	s_load_dwordx2 s[92:93], s[0:1], 0xb8
	v_lshrrev_b32_e32 v237, 6, v168
	s_nop 1
	v_readfirstlane_b32 s97, v237
	s_nop 3
	s_lshl_b32 s96, s97, 10
	s_add_u32 s96, s96, 16
	s_add_u32 s94, s81, s80
	s_cmp_lt_i32 s94, s82
	s_cselect_b32 s95, 1, 0
	s_cmp_lg_u64 s[20:21], 0
	s_cselect_b32 s95, 0, s95
	s_cmp_ge_u32 s94, 0x40
	s_cselect_b32 s97, 1, 0
	s_mul_i32 s100, s97, 0x40
	s_sub_u32 s100, s94, s100
	s_lshr_b32 s101, s100, 3
	s_and_b32 s100, s100, 7
	s_lshl_b32 s97, s97, 3
	s_add_u32 s100, s100, s97
	s_add_u32 s100, s100, s79
	s_cmp_lg_u32 s101, s74
	s_cselect_b32 s95, 0, s95
	s_cmp_eq_u32 s95, 1
	s_cselect_b32 s101, s100, s70
	s_mov_b32 s97, s101
	s_waitcnt lgkmcnt(0)
	s_lshl_b32 s94, s74, 18
	s_add_u32 s98, s92, s94
	s_addc_u32 s99, s93, 0
	s_lshl_b32 s101, s101, 18
	s_add_u32 s92, s90, s101
	s_addc_u32 s93, s91, 0
	s_lshl_b32 s94, s70, 18
	s_add_u32 s90, s90, s94
	s_addc_u32 s91, s91, 0
	s_mov_b64 s[100:101], s[90:91]
	s_mov_b64 s[90:91], s[98:99]
	s_mov_b64 s[98:99], s[92:93]
	s_mov_b64 s[92:93], s[100:101]
	s_waitcnt vmcnt(0)
	s_barrier
	s_add_u32 m0, s96, 0x0
	s_nop 0
	global_load_lds_dwordx4 v232, s[90:91]
	s_add_u32 m0, s96, 0x1000
	s_nop 0
	global_load_lds_dwordx4 v233, s[90:91]
	s_add_u32 m0, s96, 0x2000
	s_nop 0
	global_load_lds_dwordx4 v234, s[90:91]
	s_add_u32 m0, s96, 0x3000
	s_nop 0
	global_load_lds_dwordx4 v235, s[90:91]
	s_add_u32 m0, s96, 0x8000
	s_nop 0
	global_load_lds_dwordx4 v232, s[92:93]
	s_add_u32 m0, s96, 0x9000
	s_nop 0
	global_load_lds_dwordx4 v233, s[92:93]
	s_add_u32 m0, s96, 0xa000
	s_nop 0
	global_load_lds_dwordx4 v234, s[92:93]
	s_add_u32 m0, s96, 0xb000
	s_nop 0
	global_load_lds_dwordx4 v235, s[92:93]
	s_add_u32 m0, s96, 0xc000
	s_nop 0
	global_load_lds_dwordx4 v232, s[98:99]
	s_add_u32 m0, s96, 0xd000
	s_nop 0
	global_load_lds_dwordx4 v233, s[98:99]
	s_add_u32 m0, s96, 0xe000
	s_nop 0
	global_load_lds_dwordx4 v234, s[98:99]
	s_add_u32 m0, s96, 0xf000
	s_nop 0
	global_load_lds_dwordx4 v235, s[98:99]
	s_add_u32 s90, s90, 0x80
	s_addc_u32 s91, s91, 0
	s_add_u32 s92, s92, 0x80
	s_addc_u32 s93, s93, 0
	s_add_u32 s98, s98, 0x80
	s_addc_u32 s99, s99, 0
	v_mov_b32_e32 v0, 0
	v_mov_b32_e32 v1, v0
	v_mov_b32_e32 v2, v0
	v_mov_b32_e32 v3, v0
	v_mov_b32_e32 v4, v0
	v_mov_b32_e32 v5, v0
	v_mov_b32_e32 v6, v0
	v_mov_b32_e32 v7, v0
	v_mov_b32_e32 v8, v0
	v_mov_b32_e32 v9, v0
	v_mov_b32_e32 v10, v0
	v_mov_b32_e32 v11, v0
	v_mov_b32_e32 v12, v0
	v_mov_b32_e32 v13, v0
	v_mov_b32_e32 v14, v0
	v_mov_b32_e32 v15, v0
	v_mov_b32_e32 v16, v0
	v_mov_b32_e32 v17, v0
	v_mov_b32_e32 v18, v0
	v_mov_b32_e32 v19, v0
	v_mov_b32_e32 v20, v0
	v_mov_b32_e32 v21, v0
	v_mov_b32_e32 v22, v0
	v_mov_b32_e32 v23, v0
	v_mov_b32_e32 v24, v0
	v_mov_b32_e32 v25, v0
	v_mov_b32_e32 v26, v0
	v_mov_b32_e32 v27, v0
	v_mov_b32_e32 v28, v0
	v_mov_b32_e32 v29, v0
	v_mov_b32_e32 v30, v0
	v_mov_b32_e32 v31, v0
	v_mov_b32_e32 v32, v0
	v_mov_b32_e32 v33, v0
	v_mov_b32_e32 v34, v0
	v_mov_b32_e32 v35, v0
	v_mov_b32_e32 v36, v0
	v_mov_b32_e32 v37, v0
	v_mov_b32_e32 v38, v0
	v_mov_b32_e32 v39, v0
	v_mov_b32_e32 v40, v0
	v_mov_b32_e32 v41, v0
	v_mov_b32_e32 v42, v0
	v_mov_b32_e32 v43, v0
	v_mov_b32_e32 v44, v0
	v_mov_b32_e32 v45, v0
	v_mov_b32_e32 v46, v0
	v_mov_b32_e32 v47, v0
	v_mov_b32_e32 v48, v0
	v_mov_b32_e32 v49, v0
	v_mov_b32_e32 v50, v0
	v_mov_b32_e32 v51, v0
	v_mov_b32_e32 v52, v0
	v_mov_b32_e32 v53, v0
	v_mov_b32_e32 v54, v0
	v_mov_b32_e32 v55, v0
	v_mov_b32_e32 v56, v0
	v_mov_b32_e32 v57, v0
	v_mov_b32_e32 v58, v0
	v_mov_b32_e32 v59, v0
	v_mov_b32_e32 v60, v0
	v_mov_b32_e32 v61, v0
	v_mov_b32_e32 v62, v0
	v_mov_b32_e32 v63, v0
	v_mov_b32_e32 v64, v0
	v_mov_b32_e32 v65, v0
	v_mov_b32_e32 v66, v0
	v_mov_b32_e32 v67, v0
	v_mov_b32_e32 v68, v0
	v_mov_b32_e32 v69, v0
	v_mov_b32_e32 v70, v0
	v_mov_b32_e32 v71, v0
	v_mov_b32_e32 v72, v0
	v_mov_b32_e32 v73, v0
	v_mov_b32_e32 v74, v0
	v_mov_b32_e32 v75, v0
	v_mov_b32_e32 v76, v0
	v_mov_b32_e32 v77, v0
	v_mov_b32_e32 v78, v0
	v_mov_b32_e32 v79, v0
	v_mov_b32_e32 v80, v0
	v_mov_b32_e32 v81, v0
	v_mov_b32_e32 v82, v0
	v_mov_b32_e32 v83, v0
	v_mov_b32_e32 v84, v0
	v_mov_b32_e32 v85, v0
	v_mov_b32_e32 v86, v0
	v_mov_b32_e32 v87, v0
	v_mov_b32_e32 v88, v0
	v_mov_b32_e32 v89, v0
	v_mov_b32_e32 v90, v0
	v_mov_b32_e32 v91, v0
	v_mov_b32_e32 v92, v0
	v_mov_b32_e32 v93, v0
	v_mov_b32_e32 v94, v0
	v_mov_b32_e32 v95, v0
	v_mov_b32_e32 v96, v0
	v_mov_b32_e32 v97, v0
	v_mov_b32_e32 v98, v0
	v_mov_b32_e32 v99, v0
	v_mov_b32_e32 v100, v0
	v_mov_b32_e32 v101, v0
	v_mov_b32_e32 v102, v0
	v_mov_b32_e32 v103, v0
	v_mov_b32_e32 v104, v0
	v_mov_b32_e32 v105, v0
	v_mov_b32_e32 v106, v0
	v_mov_b32_e32 v107, v0
	v_mov_b32_e32 v108, v0
	v_mov_b32_e32 v109, v0
	v_mov_b32_e32 v110, v0
	v_mov_b32_e32 v111, v0
	v_mov_b32_e32 v112, v0
	v_mov_b32_e32 v113, v0
	v_mov_b32_e32 v114, v0
	v_mov_b32_e32 v115, v0
	v_mov_b32_e32 v116, v0
	v_mov_b32_e32 v117, v0
	v_mov_b32_e32 v118, v0
	v_mov_b32_e32 v119, v0
	v_mov_b32_e32 v120, v0
	v_mov_b32_e32 v121, v0
	v_mov_b32_e32 v122, v0
	v_mov_b32_e32 v123, v0
	v_mov_b32_e32 v124, v0
	v_mov_b32_e32 v125, v0
	v_mov_b32_e32 v126, v0
	v_mov_b32_e32 v127, v0
	s_mov_b32 s94, 0

.Lp6c_epdone:
	v_lshrrev_b32_e32 v236, 3, v168
	v_lshrrev_b32_e32 v237, 4, v168
	v_xor_b32_e32 v237, v237, v168
	v_and_b32_e32 v237, 7, v237
	v_lshlrev_b32_e32 v237, 4, v237
	v_lshl_or_b32 v232, v236, 11, v237
	v_add_u32_e32 v233, 0x10000, v232
	v_add_u32_e32 v234, 0x20000, v232
	v_add_u32_e32 v235, 0x30000, v232
	s_load_dwordx2 s[90:91], s[0:1], 0xa0
	s_load_dwordx2 s[92:93], s[0:1], 0xa8
	v_lshrrev_b32_e32 v237, 6, v168
	s_nop 1
	v_readfirstlane_b32 s97, v237
	s_nop 3
	s_lshl_b32 s96, s97, 10
	s_add_u32 s96, s96, 16
	s_add_u32 s94, s81, s80
	s_cmp_lt_i32 s94, s82
	s_cselect_b32 s95, 1, 0
	s_cmp_lg_u64 s[20:21], 0
	s_cselect_b32 s95, 0, s95
	s_cmp_ge_u32 s94, 0x40
	s_cselect_b32 s97, 1, 0
	s_mul_i32 s100, s97, 0x40
	s_sub_u32 s100, s94, s100
	s_lshr_b32 s101, s100, 3
	s_and_b32 s100, s100, 7
	s_lshl_b32 s97, s97, 3
	s_add_u32 s100, s100, s97
	s_add_u32 s100, s100, s79
	s_cmp_lg_u32 s101, s74
	s_cselect_b32 s95, 0, s95
	s_cmp_eq_u32 s95, 1
	s_cselect_b32 s101, s100, s70
	s_mov_b32 s97, s101
	s_waitcnt lgkmcnt(0)
	s_lshl_b32 s94, s74, 18
	s_add_u32 s94, s94, 0xe40000
	s_add_u32 s98, s92, s94
	s_addc_u32 s99, s93, 0
	s_lshl_b32 s101, s101, 18
	s_add_u32 s92, s90, s101
	s_addc_u32 s93, s91, 0
	s_lshl_b32 s94, s70, 18
	s_add_u32 s90, s90, s94
	s_addc_u32 s91, s91, 0
	s_mov_b64 s[100:101], s[90:91]
	s_mov_b64 s[90:91], s[98:99]
	s_mov_b64 s[98:99], s[92:93]
	s_mov_b64 s[92:93], s[100:101]
	s_waitcnt vmcnt(0)
	s_barrier
	s_add_u32 m0, s96, 0x0
	s_nop 0
	global_load_lds_dwordx4 v232, s[90:91]
	s_add_u32 m0, s96, 0x1000
	s_nop 0
	global_load_lds_dwordx4 v233, s[90:91]
	s_add_u32 m0, s96, 0x2000
	s_nop 0
	global_load_lds_dwordx4 v234, s[90:91]
	s_add_u32 m0, s96, 0x3000
	s_nop 0
	global_load_lds_dwordx4 v235, s[90:91]
	s_add_u32 m0, s96, 0x8000
	s_nop 0
	global_load_lds_dwordx4 v232, s[92:93]
	s_add_u32 m0, s96, 0x9000
	s_nop 0
	global_load_lds_dwordx4 v233, s[92:93]
	s_add_u32 m0, s96, 0xa000
	s_nop 0
	global_load_lds_dwordx4 v234, s[92:93]
	s_add_u32 m0, s96, 0xb000
	s_nop 0
	global_load_lds_dwordx4 v235, s[92:93]
	s_add_u32 m0, s96, 0xc000
	s_nop 0
	global_load_lds_dwordx4 v232, s[98:99]
	s_add_u32 m0, s96, 0xd000
	s_nop 0
	global_load_lds_dwordx4 v233, s[98:99]
	s_add_u32 m0, s96, 0xe000
	s_nop 0
	global_load_lds_dwordx4 v234, s[98:99]
	s_add_u32 m0, s96, 0xf000
	s_nop 0
	global_load_lds_dwordx4 v235, s[98:99]
	s_add_u32 s90, s90, 0x80
	s_addc_u32 s91, s91, 0
	s_add_u32 s92, s92, 0x80
	s_addc_u32 s93, s93, 0
	s_add_u32 s98, s98, 0x80
	s_addc_u32 s99, s99, 0
	v_mov_b32_e32 v0, 0
	v_mov_b32_e32 v1, v0
	v_mov_b32_e32 v2, v0
	v_mov_b32_e32 v3, v0
	v_mov_b32_e32 v4, v0
	v_mov_b32_e32 v5, v0
	v_mov_b32_e32 v6, v0
	v_mov_b32_e32 v7, v0
	v_mov_b32_e32 v8, v0
	v_mov_b32_e32 v9, v0
	v_mov_b32_e32 v10, v0
	v_mov_b32_e32 v11, v0
	v_mov_b32_e32 v12, v0
	v_mov_b32_e32 v13, v0
	v_mov_b32_e32 v14, v0
	v_mov_b32_e32 v15, v0
	v_mov_b32_e32 v16, v0
	v_mov_b32_e32 v17, v0
	v_mov_b32_e32 v18, v0
	v_mov_b32_e32 v19, v0
	v_mov_b32_e32 v20, v0
	v_mov_b32_e32 v21, v0
	v_mov_b32_e32 v22, v0
	v_mov_b32_e32 v23, v0
	v_mov_b32_e32 v24, v0
	v_mov_b32_e32 v25, v0
	v_mov_b32_e32 v26, v0
	v_mov_b32_e32 v27, v0
	v_mov_b32_e32 v28, v0
	v_mov_b32_e32 v29, v0
	v_mov_b32_e32 v30, v0
	v_mov_b32_e32 v31, v0
	v_mov_b32_e32 v32, v0
	v_mov_b32_e32 v33, v0
	v_mov_b32_e32 v34, v0
	v_mov_b32_e32 v35, v0
	v_mov_b32_e32 v36, v0
	v_mov_b32_e32 v37, v0
	v_mov_b32_e32 v38, v0
	v_mov_b32_e32 v39, v0
	v_mov_b32_e32 v40, v0
	v_mov_b32_e32 v41, v0
	v_mov_b32_e32 v42, v0
	v_mov_b32_e32 v43, v0
	v_mov_b32_e32 v44, v0
	v_mov_b32_e32 v45, v0
	v_mov_b32_e32 v46, v0
	v_mov_b32_e32 v47, v0
	v_mov_b32_e32 v48, v0
	v_mov_b32_e32 v49, v0
	v_mov_b32_e32 v50, v0
	v_mov_b32_e32 v51, v0
	v_mov_b32_e32 v52, v0
	v_mov_b32_e32 v53, v0
	v_mov_b32_e32 v54, v0
	v_mov_b32_e32 v55, v0
	v_mov_b32_e32 v56, v0
	v_mov_b32_e32 v57, v0
	v_mov_b32_e32 v58, v0
	v_mov_b32_e32 v59, v0
	v_mov_b32_e32 v60, v0
	v_mov_b32_e32 v61, v0
	v_mov_b32_e32 v62, v0
	v_mov_b32_e32 v63, v0
	v_mov_b32_e32 v64, v0
	v_mov_b32_e32 v65, v0
	v_mov_b32_e32 v66, v0
	v_mov_b32_e32 v67, v0
	v_mov_b32_e32 v68, v0
	v_mov_b32_e32 v69, v0
	v_mov_b32_e32 v70, v0
	v_mov_b32_e32 v71, v0
	v_mov_b32_e32 v72, v0
	v_mov_b32_e32 v73, v0
	v_mov_b32_e32 v74, v0
	v_mov_b32_e32 v75, v0
	v_mov_b32_e32 v76, v0
	v_mov_b32_e32 v77, v0
	v_mov_b32_e32 v78, v0
	v_mov_b32_e32 v79, v0
	v_mov_b32_e32 v80, v0
	v_mov_b32_e32 v81, v0
	v_mov_b32_e32 v82, v0
	v_mov_b32_e32 v83, v0
	v_mov_b32_e32 v84, v0
	v_mov_b32_e32 v85, v0
	v_mov_b32_e32 v86, v0
	v_mov_b32_e32 v87, v0
	v_mov_b32_e32 v88, v0
	v_mov_b32_e32 v89, v0
	v_mov_b32_e32 v90, v0
	v_mov_b32_e32 v91, v0
	v_mov_b32_e32 v92, v0
	v_mov_b32_e32 v93, v0
	v_mov_b32_e32 v94, v0
	v_mov_b32_e32 v95, v0
	v_mov_b32_e32 v96, v0
	v_mov_b32_e32 v97, v0
	v_mov_b32_e32 v98, v0
	v_mov_b32_e32 v99, v0
	v_mov_b32_e32 v100, v0
	v_mov_b32_e32 v101, v0
	v_mov_b32_e32 v102, v0
	v_mov_b32_e32 v103, v0
	v_mov_b32_e32 v104, v0
	v_mov_b32_e32 v105, v0
	v_mov_b32_e32 v106, v0
	v_mov_b32_e32 v107, v0
	v_mov_b32_e32 v108, v0
	v_mov_b32_e32 v109, v0
	v_mov_b32_e32 v110, v0
	v_mov_b32_e32 v111, v0
	v_mov_b32_e32 v112, v0
	v_mov_b32_e32 v113, v0
	v_mov_b32_e32 v114, v0
	v_mov_b32_e32 v115, v0
	v_mov_b32_e32 v116, v0
	v_mov_b32_e32 v117, v0
	v_mov_b32_e32 v118, v0
	v_mov_b32_e32 v119, v0
	v_mov_b32_e32 v120, v0
	v_mov_b32_e32 v121, v0
	v_mov_b32_e32 v122, v0
	v_mov_b32_e32 v123, v0
	v_mov_b32_e32 v124, v0
	v_mov_b32_e32 v125, v0
	v_mov_b32_e32 v126, v0
	v_mov_b32_e32 v127, v0
	s_mov_b32 s94, 0
